# grid barrier: non-leader workgroups poll the cross-XCD release word directly (one release hop less); leaders' local release atomics dropped
# speedup vs baseline: 1.0009x; 1.0009x over previous
.LBB0_189:
	s_or_b64 exec, exec, s[28:29]
	v_cvt_f32_u32_e32 v4, v2
	s_waitcnt vmcnt(0)
	v_readfirstlane_b32 s3, v3
	v_sub_u32_e32 v3, 0, v2
	v_rcp_iflag_f32_e32 v4, v4
	v_add_u32_e32 v5, s3, v1
	v_mul_f32_e32 v4, 0x4f7ffffe, v4
	v_cvt_u32_f32_e32 v4, v4
	v_mul_lo_u32 v1, v3, v4
	v_mul_hi_u32 v1, v4, v1
	v_add_u32_e32 v1, v4, v1
	v_mul_hi_u32 v1, v5, v1
	v_mul_lo_u32 v3, v1, v2
	v_sub_u32_e32 v3, v5, v3
	v_add_u32_e32 v4, 1, v1
	v_cmp_ge_u32_e32 vcc, v3, v2
	s_nop 1
	v_cndmask_b32_e32 v1, v1, v4, vcc
	v_sub_u32_e32 v4, v3, v2
	v_cndmask_b32_e32 v3, v3, v4, vcc
	v_add_u32_e32 v4, 1, v1
	v_cmp_ge_u32_e32 vcc, v3, v2
	v_add_u32_e32 v3, 1, v5
	s_nop 0
	v_cndmask_b32_e32 v1, v1, v4, vcc
	v_mul_lo_u32 v4, v2, v1
	v_add_u32_e32 v2, v4, v2
	v_cmp_ne_u32_e32 vcc, v3, v2
	s_and_saveexec_b64 s[10:11], vcc
	s_xor_b64 s[10:11], exec, s[10:11]
	s_cbranch_execz .LBB0_203
	s_waitcnt lgkmcnt(0)
	v_mov_b32_e32 v0, 0
	s_add_u32 s58, s56, 0x13dad500
	s_addc_u32 s59, s57, 0
	global_load_dword v0, v0, s[58:59] sc1
	s_waitcnt vmcnt(0)
	v_cmp_eq_u32_e32 vcc, v0, v1
	s_and_saveexec_b64 s[28:29], vcc
	s_cbranch_execz .LBB0_202
	s_add_u32 s34, s56, 0x13daa200
	s_addc_u32 s35, s57, 0
	s_mov_b32 s3, 1
	s_mov_b64 s[60:61], 0
	v_mov_b32_e32 v0, 0
	s_branch .LBB0_193

.LBB0_220:
	s_or_b64 exec, exec, s[28:29]
	s_mov_b64 s[28:29], exec
	v_mbcnt_lo_u32_b32 v0, s28, 0
	v_mbcnt_hi_u32_b32 v0, s29, v0
	v_cmp_eq_u32_e32 vcc, 0, v0
	s_waitcnt vmcnt(0)
	buffer_inv sc1
	s_and_saveexec_b64 s[34:35], vcc
	s_cbranch_execz .LBB0_222
	s_bcnt1_i32_b64 s3, s[28:29]
	v_mov_b32_e32 v0, 0x2000
	v_mov_b32_e32 v1, s3
.LBB0_222:
	s_or_b64 exec, exec, s[34:35]
	s_waitcnt vmcnt(0)

.LBB0_382:
	s_or_b64 exec, exec, s[10:11]
	v_cvt_f32_u32_e32 v4, v2
	s_waitcnt vmcnt(0)
	v_readfirstlane_b32 s3, v3
	v_sub_u32_e32 v3, 0, v2
	v_rcp_iflag_f32_e32 v4, v4
	v_add_u32_e32 v5, s3, v1
	v_mul_f32_e32 v4, 0x4f7ffffe, v4
	v_cvt_u32_f32_e32 v4, v4
	v_mul_lo_u32 v1, v3, v4
	v_mul_hi_u32 v1, v4, v1
	v_add_u32_e32 v1, v4, v1
	v_mul_hi_u32 v1, v5, v1
	v_mul_lo_u32 v3, v1, v2
	v_sub_u32_e32 v3, v5, v3
	v_add_u32_e32 v4, 1, v1
	v_cmp_ge_u32_e32 vcc, v3, v2
	s_nop 1
	v_cndmask_b32_e32 v1, v1, v4, vcc
	v_sub_u32_e32 v4, v3, v2
	v_cndmask_b32_e32 v3, v3, v4, vcc
	v_add_u32_e32 v4, 1, v1
	v_cmp_ge_u32_e32 vcc, v3, v2
	v_add_u32_e32 v3, 1, v5
	s_nop 0
	v_cndmask_b32_e32 v1, v1, v4, vcc
	v_mul_lo_u32 v4, v2, v1
	v_add_u32_e32 v2, v4, v2
	v_cmp_ne_u32_e32 vcc, v3, v2
	s_and_saveexec_b64 s[8:9], vcc
	s_xor_b64 s[8:9], exec, s[8:9]
	s_cbranch_execz .LBB0_396
	s_waitcnt lgkmcnt(0)
	v_mov_b32_e32 v0, 0
	s_add_u32 s22, s56, 0x13dad500
	s_addc_u32 s23, s57, 0
	global_load_dword v0, v0, s[22:23] sc1
	s_waitcnt vmcnt(0)
	v_cmp_eq_u32_e32 vcc, v0, v1
	s_and_saveexec_b64 s[10:11], vcc
	s_cbranch_execz .LBB0_395
	s_add_u32 s20, s56, 0x13daa200
	s_addc_u32 s21, s57, 0
	s_mov_b32 s3, 1
	s_mov_b64 s[28:29], 0
	v_mov_b32_e32 v0, 0
	s_branch .LBB0_386

.LBB0_413:
	s_or_b64 exec, exec, s[8:9]
	s_mov_b64 s[8:9], exec
	v_mbcnt_lo_u32_b32 v0, s8, 0
	v_mbcnt_hi_u32_b32 v0, s9, v0
	v_cmp_eq_u32_e32 vcc, 0, v0
	s_waitcnt vmcnt(0)
	buffer_inv sc1
	s_and_saveexec_b64 s[10:11], vcc
	s_cbranch_execz .LBB0_415
	s_bcnt1_i32_b64 s3, s[8:9]
	v_mov_b32_e32 v0, 0x2000
	v_mov_b32_e32 v1, s3
.LBB0_415:
	s_or_b64 exec, exec, s[10:11]
	s_waitcnt vmcnt(0)

.LBB0_488:
	s_or_b64 exec, exec, s[16:17]
	v_cvt_f32_u32_e32 v4, v2
	s_waitcnt vmcnt(0)
	v_readfirstlane_b32 s3, v3
	v_sub_u32_e32 v3, 0, v2
	v_rcp_iflag_f32_e32 v4, v4
	v_add_u32_e32 v5, s3, v1
	v_mul_f32_e32 v4, 0x4f7ffffe, v4
	v_cvt_u32_f32_e32 v4, v4
	v_mul_lo_u32 v1, v3, v4
	v_mul_hi_u32 v1, v4, v1
	v_add_u32_e32 v1, v4, v1
	v_mul_hi_u32 v1, v5, v1
	v_mul_lo_u32 v3, v1, v2
	v_sub_u32_e32 v3, v5, v3
	v_add_u32_e32 v4, 1, v1
	v_cmp_ge_u32_e32 vcc, v3, v2
	s_nop 1
	v_cndmask_b32_e32 v1, v1, v4, vcc
	v_sub_u32_e32 v4, v3, v2
	v_cndmask_b32_e32 v3, v3, v4, vcc
	v_add_u32_e32 v4, 1, v1
	v_cmp_ge_u32_e32 vcc, v3, v2
	v_add_u32_e32 v3, 1, v5
	s_nop 0
	v_cndmask_b32_e32 v1, v1, v4, vcc
	v_mul_lo_u32 v4, v2, v1
	v_add_u32_e32 v2, v4, v2
	v_cmp_ne_u32_e32 vcc, v3, v2
	s_and_saveexec_b64 s[10:11], vcc
	s_xor_b64 s[10:11], exec, s[10:11]
	s_cbranch_execz .LBB0_502
	s_waitcnt lgkmcnt(0)
	v_mov_b32_e32 v0, 0
	s_add_u32 s20, s56, 0x13dad500
	s_addc_u32 s21, s57, 0
	global_load_dword v0, v0, s[20:21] sc1
	s_waitcnt vmcnt(0)
	v_cmp_eq_u32_e32 vcc, v0, v1
	s_and_saveexec_b64 s[16:17], vcc
	s_cbranch_execz .LBB0_501
	s_add_u32 s18, s56, 0x13daa200
	s_addc_u32 s19, s57, 0
	s_mov_b32 s3, 1
	s_mov_b64 s[22:23], 0
	v_mov_b32_e32 v0, 0
	s_branch .LBB0_492

.LBB0_519:
	s_or_b64 exec, exec, s[16:17]
	s_mov_b64 s[16:17], exec
	v_mbcnt_lo_u32_b32 v0, s16, 0
	v_mbcnt_hi_u32_b32 v0, s17, v0
	v_cmp_eq_u32_e32 vcc, 0, v0
	s_waitcnt vmcnt(0)
	buffer_inv sc1
	s_and_saveexec_b64 s[18:19], vcc
	s_cbranch_execz .LBB0_521
	s_bcnt1_i32_b64 s3, s[16:17]
	v_mov_b32_e32 v0, 0x2000
	v_mov_b32_e32 v1, s3
.LBB0_521:
	s_or_b64 exec, exec, s[18:19]
	s_waitcnt vmcnt(0)

.LBB0_600:
	s_or_b64 exec, exec, s[10:11]
	v_cvt_f32_u32_e32 v4, v2
	s_waitcnt vmcnt(0)
	v_readfirstlane_b32 s3, v3
	v_sub_u32_e32 v3, 0, v2
	v_rcp_iflag_f32_e32 v4, v4
	v_add_u32_e32 v5, s3, v1
	v_mul_f32_e32 v4, 0x4f7ffffe, v4
	v_cvt_u32_f32_e32 v4, v4
	v_mul_lo_u32 v1, v3, v4
	v_mul_hi_u32 v1, v4, v1
	v_add_u32_e32 v1, v4, v1
	v_mul_hi_u32 v1, v5, v1
	v_mul_lo_u32 v3, v1, v2
	v_sub_u32_e32 v3, v5, v3
	v_add_u32_e32 v4, 1, v1
	v_cmp_ge_u32_e32 vcc, v3, v2
	s_nop 1
	v_cndmask_b32_e32 v1, v1, v4, vcc
	v_sub_u32_e32 v4, v3, v2
	v_cndmask_b32_e32 v3, v3, v4, vcc
	v_add_u32_e32 v4, 1, v1
	v_cmp_ge_u32_e32 vcc, v3, v2
	v_add_u32_e32 v3, 1, v5
	s_nop 0
	v_cndmask_b32_e32 v1, v1, v4, vcc
	v_mul_lo_u32 v4, v2, v1
	v_add_u32_e32 v2, v4, v2
	v_cmp_ne_u32_e32 vcc, v3, v2
	s_and_saveexec_b64 s[8:9], vcc
	s_xor_b64 s[8:9], exec, s[8:9]
	s_cbranch_execz .LBB0_614
	s_waitcnt lgkmcnt(0)
	v_mov_b32_e32 v0, 0
	s_add_u32 s18, s56, 0x13dad500
	s_addc_u32 s19, s57, 0
	global_load_dword v0, v0, s[18:19] sc1
	s_waitcnt vmcnt(0)
	v_cmp_eq_u32_e32 vcc, v0, v1
	s_and_saveexec_b64 s[10:11], vcc
	s_cbranch_execz .LBB0_613
	s_add_u32 s16, s56, 0x13daa200
	s_addc_u32 s17, s57, 0
	s_mov_b32 s3, 1
	s_mov_b64 s[20:21], 0
	v_mov_b32_e32 v0, 0
	s_branch .LBB0_604

.LBB0_631:
	s_or_b64 exec, exec, s[8:9]
	s_mov_b64 s[8:9], exec
	v_mbcnt_lo_u32_b32 v0, s8, 0
	v_mbcnt_hi_u32_b32 v0, s9, v0
	v_cmp_eq_u32_e32 vcc, 0, v0
	s_waitcnt vmcnt(0)
	buffer_inv sc1
	s_and_saveexec_b64 s[10:11], vcc
	s_cbranch_execz .LBB0_633
	s_bcnt1_i32_b64 s3, s[8:9]
	v_mov_b32_e32 v0, 0x2000
	v_mov_b32_e32 v1, s3
.LBB0_633:
	s_or_b64 exec, exec, s[10:11]
	s_waitcnt vmcnt(0)

.LBB0_695:
	s_or_b64 exec, exec, s[10:11]
	v_cvt_f32_u32_e32 v4, v2
	s_waitcnt vmcnt(0)
	v_readfirstlane_b32 s3, v3
	v_sub_u32_e32 v3, 0, v2
	v_rcp_iflag_f32_e32 v4, v4
	v_add_u32_e32 v5, s3, v1
	v_mul_f32_e32 v4, 0x4f7ffffe, v4
	v_cvt_u32_f32_e32 v4, v4
	v_mul_lo_u32 v1, v3, v4
	v_mul_hi_u32 v1, v4, v1
	v_add_u32_e32 v1, v4, v1
	v_mul_hi_u32 v1, v5, v1
	v_mul_lo_u32 v3, v1, v2
	v_sub_u32_e32 v3, v5, v3
	v_add_u32_e32 v4, 1, v1
	v_cmp_ge_u32_e32 vcc, v3, v2
	s_nop 1
	v_cndmask_b32_e32 v1, v1, v4, vcc
	v_sub_u32_e32 v4, v3, v2
	v_cndmask_b32_e32 v3, v3, v4, vcc
	v_add_u32_e32 v4, 1, v1
	v_cmp_ge_u32_e32 vcc, v3, v2
	v_add_u32_e32 v3, 1, v5
	s_nop 0
	v_cndmask_b32_e32 v1, v1, v4, vcc
	v_mul_lo_u32 v4, v2, v1
	v_add_u32_e32 v2, v4, v2
	v_cmp_ne_u32_e32 vcc, v3, v2
	s_and_saveexec_b64 s[8:9], vcc
	s_xor_b64 s[8:9], exec, s[8:9]
	s_cbranch_execz .LBB0_709
	s_waitcnt lgkmcnt(0)
	v_mov_b32_e32 v0, 0
	s_add_u32 s16, s56, 0x13dad500
	s_addc_u32 s17, s57, 0
	global_load_dword v0, v0, s[16:17] sc1
	s_waitcnt vmcnt(0)
	v_cmp_eq_u32_e32 vcc, v0, v1
	s_and_saveexec_b64 s[10:11], vcc
	s_cbranch_execz .LBB0_708
	s_add_u32 s12, s56, 0x13daa200
	s_addc_u32 s13, s57, 0
	s_mov_b32 s3, 1
	s_mov_b64 s[18:19], 0
	v_mov_b32_e32 v0, 0
	s_branch .LBB0_699

.LBB0_726:
	s_or_b64 exec, exec, s[8:9]
	s_mov_b64 s[8:9], exec
	v_mbcnt_lo_u32_b32 v0, s8, 0
	v_mbcnt_hi_u32_b32 v0, s9, v0
	v_cmp_eq_u32_e32 vcc, 0, v0
	s_waitcnt vmcnt(0)
	buffer_inv sc1
	s_and_saveexec_b64 s[10:11], vcc
	s_cbranch_execz .LBB0_728
	s_bcnt1_i32_b64 s3, s[8:9]
	v_mov_b32_e32 v0, 0x2000
	v_mov_b32_e32 v1, s3
.LBB0_728:
	s_or_b64 exec, exec, s[10:11]
	s_waitcnt vmcnt(0)
